# final RMSNorm: all eight rows' loads of a wave issued up front (generic one-row-ahead loop kept as fallback)
# speedup vs baseline: 1.0093x; 1.0017x over previous
.LBB0_1386:
	global_load_dwordx4 v[20:23], v[0:1], off
	global_load_dwordx4 v[24:27], v[0:1], off offset:1024
	global_load_dwordx4 v[28:31], v[0:1], off offset:2048
	global_load_dwordx4 v[32:35], v[0:1], off offset:3072
	s_cmpk_lg_u32 s12, 0x800
	s_cbranch_scc1 .Lfn_generic
	s_cmpk_gt_u32 s8, 0x7ff
	s_cbranch_scc1 .Lfn_generic
	v_mov_b32_e32 v132, 0
	v_mov_b32_e32 v133, 0
	v_mov_b32_e32 v134, 0
	v_mov_b32_e32 v135, 0
	v_mov_b32_e32 v136, 0
	v_mov_b32_e32 v137, 0
	v_mov_b32_e32 v138, 0
	v_mov_b32_e32 v139, 0
	s_and_saveexec_b64 s[0:1], vcc
	global_load_dword v132, v[2:3], off
	v_lshl_add_u64 v[2:3], v[2:3], 0, s[2:3]
	global_load_dword v133, v[2:3], off
	v_lshl_add_u64 v[2:3], v[2:3], 0, s[2:3]
	global_load_dword v134, v[2:3], off
	v_lshl_add_u64 v[2:3], v[2:3], 0, s[2:3]
	global_load_dword v135, v[2:3], off
	v_lshl_add_u64 v[2:3], v[2:3], 0, s[2:3]
	global_load_dword v136, v[2:3], off
	v_lshl_add_u64 v[2:3], v[2:3], 0, s[2:3]
	global_load_dword v137, v[2:3], off
	v_lshl_add_u64 v[2:3], v[2:3], 0, s[2:3]
	global_load_dword v138, v[2:3], off
	v_lshl_add_u64 v[2:3], v[2:3], 0, s[2:3]
	global_load_dword v139, v[2:3], off
	s_or_b64 exec, exec, s[0:1]
	global_load_dwordx2 v[60:61], v[4:5], off offset:-1024
	global_load_dwordx2 v[62:63], v[4:5], off offset:-512
	global_load_dwordx2 v[64:65], v[4:5], off
	global_load_dwordx2 v[66:67], v[4:5], off offset:512
	v_lshl_add_u64 v[4:5], v[4:5], 0, s[4:5]
	global_load_dwordx2 v[68:69], v[4:5], off offset:-1024
	global_load_dwordx2 v[70:71], v[4:5], off offset:-512
	global_load_dwordx2 v[72:73], v[4:5], off
	global_load_dwordx2 v[74:75], v[4:5], off offset:512
	v_lshl_add_u64 v[4:5], v[4:5], 0, s[4:5]
	global_load_dwordx2 v[76:77], v[4:5], off offset:-1024
	global_load_dwordx2 v[78:79], v[4:5], off offset:-512
	global_load_dwordx2 v[80:81], v[4:5], off
	global_load_dwordx2 v[82:83], v[4:5], off offset:512
	v_lshl_add_u64 v[4:5], v[4:5], 0, s[4:5]
	global_load_dwordx2 v[84:85], v[4:5], off offset:-1024
	global_load_dwordx2 v[86:87], v[4:5], off offset:-512
	global_load_dwordx2 v[88:89], v[4:5], off
	global_load_dwordx2 v[90:91], v[4:5], off offset:512
	v_lshl_add_u64 v[4:5], v[4:5], 0, s[4:5]
	global_load_dwordx2 v[92:93], v[4:5], off offset:-1024
	global_load_dwordx2 v[94:95], v[4:5], off offset:-512
	global_load_dwordx2 v[96:97], v[4:5], off
	global_load_dwordx2 v[98:99], v[4:5], off offset:512
	v_lshl_add_u64 v[4:5], v[4:5], 0, s[4:5]
	global_load_dwordx2 v[100:101], v[4:5], off offset:-1024
	global_load_dwordx2 v[102:103], v[4:5], off offset:-512
	global_load_dwordx2 v[104:105], v[4:5], off
	global_load_dwordx2 v[106:107], v[4:5], off offset:512
	v_lshl_add_u64 v[4:5], v[4:5], 0, s[4:5]
	global_load_dwordx2 v[108:109], v[4:5], off offset:-1024
	global_load_dwordx2 v[110:111], v[4:5], off offset:-512
	global_load_dwordx2 v[112:113], v[4:5], off
	global_load_dwordx2 v[114:115], v[4:5], off offset:512
	v_lshl_add_u64 v[4:5], v[4:5], 0, s[4:5]
	global_load_dwordx2 v[116:117], v[4:5], off offset:-1024
	global_load_dwordx2 v[118:119], v[4:5], off offset:-512
	global_load_dwordx2 v[120:121], v[4:5], off
	global_load_dwordx2 v[122:123], v[4:5], off offset:512
	s_waitcnt vmcnt(28)
	ds_swizzle_b32 v16, v132 offset:swizzle(SWAP,1)
	s_waitcnt lgkmcnt(0)
	v_add_f32_e32 v9, v132, v16
	ds_swizzle_b32 v16, v9 offset:swizzle(SWAP,2)
	s_waitcnt lgkmcnt(0)
	v_add_f32_e32 v9, v9, v16
	ds_swizzle_b32 v16, v9 offset:swizzle(SWAP,4)
	s_waitcnt lgkmcnt(0)
	v_add_f32_e32 v9, v9, v16
	ds_swizzle_b32 v16, v9 offset:swizzle(SWAP,8)
	s_waitcnt lgkmcnt(0)
	v_add_f32_e32 v9, v9, v16
	ds_swizzle_b32 v16, v9 offset:swizzle(SWAP,16)
	s_waitcnt lgkmcnt(0)
	v_add_f32_e32 v9, v9, v16
	v_mov_b32_e32 v16, v9
	s_nop 1
	v_permlane32_swap_b32_e32 v9, v16
	v_add_f32_e32 v9, v9, v16
	v_fmamk_f32 v9, v9, 0x3a800000, v8
	v_mul_f32_e32 v16, 0x4b800000, v9
	v_cmp_gt_f32_e64 s[0:1], s9, v9
	v_lshlrev_b32_e32 v18, 16, v60
	v_cndmask_b32_e64 v9, v9, v16, s[0:1]
	v_rsq_f32_e32 v9, v9
	v_and_b32_e32 v19, 0xffff0000, v60
	v_lshlrev_b32_e32 v60, 16, v61
	v_and_b32_e32 v61, 0xffff0000, v61
	v_mul_f32_e32 v16, 0x45800000, v9
	v_cndmask_b32_e64 v16, v9, v16, s[0:1]
	v_pk_mul_f32 v[18:19], v[16:17], v[18:19] op_sel_hi:[0,1]
	v_pk_mul_f32 v[60:61], v[16:17], v[60:61] op_sel_hi:[0,1]
	v_pk_mul_f32 v[12:13], v[22:23], v[60:61]
	v_pk_mul_f32 v[10:11], v[20:21], v[18:19]
	v_lshlrev_b32_e32 v18, 16, v62
	v_and_b32_e32 v19, 0xffff0000, v62
	v_lshlrev_b32_e32 v62, 16, v63
	v_and_b32_e32 v63, 0xffff0000, v63
	v_pk_mul_f32 v[18:19], v[16:17], v[18:19] op_sel_hi:[0,1]
	v_pk_mul_f32 v[62:63], v[16:17], v[62:63] op_sel_hi:[0,1]
	v_pk_mul_f32 v[44:45], v[26:27], v[62:63]
	v_pk_mul_f32 v[42:43], v[24:25], v[18:19]
	v_lshlrev_b32_e32 v18, 16, v64
	v_and_b32_e32 v19, 0xffff0000, v64
	v_lshlrev_b32_e32 v64, 16, v65
	v_and_b32_e32 v65, 0xffff0000, v65
	v_pk_mul_f32 v[18:19], v[16:17], v[18:19] op_sel_hi:[0,1]
	v_pk_mul_f32 v[64:65], v[16:17], v[64:65] op_sel_hi:[0,1]
	v_pk_mul_f32 v[48:49], v[30:31], v[64:65]
	v_pk_mul_f32 v[46:47], v[28:29], v[18:19]
	v_lshlrev_b32_e32 v18, 16, v66
	v_and_b32_e32 v19, 0xffff0000, v66
	v_lshlrev_b32_e32 v66, 16, v67
	v_and_b32_e32 v67, 0xffff0000, v67
	v_pk_mul_f32 v[18:19], v[16:17], v[18:19] op_sel_hi:[0,1]
	v_pk_mul_f32 v[66:67], v[16:17], v[66:67] op_sel_hi:[0,1]
	v_pk_mul_f32 v[52:53], v[34:35], v[66:67]
	v_pk_mul_f32 v[50:51], v[32:33], v[18:19]
	global_store_dwordx4 v[6:7], v[10:13], off offset:-2048
	global_store_dwordx4 v[6:7], v[42:45], off offset:-1024
	global_store_dwordx4 v[6:7], v[46:49], off
	global_store_dwordx4 v[6:7], v[50:53], off offset:1024
	v_lshl_add_u64 v[6:7], v[6:7], 0, s[6:7]
	s_waitcnt vmcnt(28)
	ds_swizzle_b32 v16, v133 offset:swizzle(SWAP,1)
	s_waitcnt lgkmcnt(0)
	v_add_f32_e32 v9, v133, v16
	ds_swizzle_b32 v16, v9 offset:swizzle(SWAP,2)
	s_waitcnt lgkmcnt(0)
	v_add_f32_e32 v9, v9, v16
	ds_swizzle_b32 v16, v9 offset:swizzle(SWAP,4)
	s_waitcnt lgkmcnt(0)
	v_add_f32_e32 v9, v9, v16
	ds_swizzle_b32 v16, v9 offset:swizzle(SWAP,8)
	s_waitcnt lgkmcnt(0)
	v_add_f32_e32 v9, v9, v16
	ds_swizzle_b32 v16, v9 offset:swizzle(SWAP,16)
	s_waitcnt lgkmcnt(0)
	v_add_f32_e32 v9, v9, v16
	v_mov_b32_e32 v16, v9
	s_nop 1
	v_permlane32_swap_b32_e32 v9, v16
	v_add_f32_e32 v9, v9, v16
	v_fmamk_f32 v9, v9, 0x3a800000, v8
	v_mul_f32_e32 v16, 0x4b800000, v9
	v_cmp_gt_f32_e64 s[0:1], s9, v9
	v_lshlrev_b32_e32 v18, 16, v68
	v_cndmask_b32_e64 v9, v9, v16, s[0:1]
	v_rsq_f32_e32 v9, v9
	v_and_b32_e32 v19, 0xffff0000, v68
	v_lshlrev_b32_e32 v68, 16, v69
	v_and_b32_e32 v69, 0xffff0000, v69
	v_mul_f32_e32 v16, 0x45800000, v9
	v_cndmask_b32_e64 v16, v9, v16, s[0:1]
	v_pk_mul_f32 v[18:19], v[16:17], v[18:19] op_sel_hi:[0,1]
	v_pk_mul_f32 v[68:69], v[16:17], v[68:69] op_sel_hi:[0,1]
	v_pk_mul_f32 v[12:13], v[22:23], v[68:69]
	v_pk_mul_f32 v[10:11], v[20:21], v[18:19]
	v_lshlrev_b32_e32 v18, 16, v70
	v_and_b32_e32 v19, 0xffff0000, v70
	v_lshlrev_b32_e32 v70, 16, v71
	v_and_b32_e32 v71, 0xffff0000, v71
	v_pk_mul_f32 v[18:19], v[16:17], v[18:19] op_sel_hi:[0,1]
	v_pk_mul_f32 v[70:71], v[16:17], v[70:71] op_sel_hi:[0,1]
	v_pk_mul_f32 v[44:45], v[26:27], v[70:71]
	v_pk_mul_f32 v[42:43], v[24:25], v[18:19]
	v_lshlrev_b32_e32 v18, 16, v72
	v_and_b32_e32 v19, 0xffff0000, v72
	v_lshlrev_b32_e32 v72, 16, v73
	v_and_b32_e32 v73, 0xffff0000, v73
	v_pk_mul_f32 v[18:19], v[16:17], v[18:19] op_sel_hi:[0,1]
	v_pk_mul_f32 v[72:73], v[16:17], v[72:73] op_sel_hi:[0,1]
	v_pk_mul_f32 v[48:49], v[30:31], v[72:73]
	v_pk_mul_f32 v[46:47], v[28:29], v[18:19]
	v_lshlrev_b32_e32 v18, 16, v74
	v_and_b32_e32 v19, 0xffff0000, v74
	v_lshlrev_b32_e32 v74, 16, v75
	v_and_b32_e32 v75, 0xffff0000, v75
	v_pk_mul_f32 v[18:19], v[16:17], v[18:19] op_sel_hi:[0,1]
	v_pk_mul_f32 v[74:75], v[16:17], v[74:75] op_sel_hi:[0,1]
	v_pk_mul_f32 v[52:53], v[34:35], v[74:75]
	v_pk_mul_f32 v[50:51], v[32:33], v[18:19]
	global_store_dwordx4 v[6:7], v[10:13], off offset:-2048
	global_store_dwordx4 v[6:7], v[42:45], off offset:-1024
	global_store_dwordx4 v[6:7], v[46:49], off
	global_store_dwordx4 v[6:7], v[50:53], off offset:1024
	v_lshl_add_u64 v[6:7], v[6:7], 0, s[6:7]
	s_waitcnt vmcnt(28)
	ds_swizzle_b32 v16, v134 offset:swizzle(SWAP,1)
	s_waitcnt lgkmcnt(0)
	v_add_f32_e32 v9, v134, v16
	ds_swizzle_b32 v16, v9 offset:swizzle(SWAP,2)
	s_waitcnt lgkmcnt(0)
	v_add_f32_e32 v9, v9, v16
	ds_swizzle_b32 v16, v9 offset:swizzle(SWAP,4)
	s_waitcnt lgkmcnt(0)
	v_add_f32_e32 v9, v9, v16
	ds_swizzle_b32 v16, v9 offset:swizzle(SWAP,8)
	s_waitcnt lgkmcnt(0)
	v_add_f32_e32 v9, v9, v16
	ds_swizzle_b32 v16, v9 offset:swizzle(SWAP,16)
	s_waitcnt lgkmcnt(0)
	v_add_f32_e32 v9, v9, v16
	v_mov_b32_e32 v16, v9
	s_nop 1
	v_permlane32_swap_b32_e32 v9, v16
	v_add_f32_e32 v9, v9, v16
	v_fmamk_f32 v9, v9, 0x3a800000, v8
	v_mul_f32_e32 v16, 0x4b800000, v9
	v_cmp_gt_f32_e64 s[0:1], s9, v9
	v_lshlrev_b32_e32 v18, 16, v76
	v_cndmask_b32_e64 v9, v9, v16, s[0:1]
	v_rsq_f32_e32 v9, v9
	v_and_b32_e32 v19, 0xffff0000, v76
	v_lshlrev_b32_e32 v76, 16, v77
	v_and_b32_e32 v77, 0xffff0000, v77
	v_mul_f32_e32 v16, 0x45800000, v9
	v_cndmask_b32_e64 v16, v9, v16, s[0:1]
	v_pk_mul_f32 v[18:19], v[16:17], v[18:19] op_sel_hi:[0,1]
	v_pk_mul_f32 v[76:77], v[16:17], v[76:77] op_sel_hi:[0,1]
	v_pk_mul_f32 v[12:13], v[22:23], v[76:77]
	v_pk_mul_f32 v[10:11], v[20:21], v[18:19]
	v_lshlrev_b32_e32 v18, 16, v78
	v_and_b32_e32 v19, 0xffff0000, v78
	v_lshlrev_b32_e32 v78, 16, v79
	v_and_b32_e32 v79, 0xffff0000, v79
	v_pk_mul_f32 v[18:19], v[16:17], v[18:19] op_sel_hi:[0,1]
	v_pk_mul_f32 v[78:79], v[16:17], v[78:79] op_sel_hi:[0,1]
	v_pk_mul_f32 v[44:45], v[26:27], v[78:79]
	v_pk_mul_f32 v[42:43], v[24:25], v[18:19]
	v_lshlrev_b32_e32 v18, 16, v80
	v_and_b32_e32 v19, 0xffff0000, v80
	v_lshlrev_b32_e32 v80, 16, v81
	v_and_b32_e32 v81, 0xffff0000, v81
	v_pk_mul_f32 v[18:19], v[16:17], v[18:19] op_sel_hi:[0,1]
	v_pk_mul_f32 v[80:81], v[16:17], v[80:81] op_sel_hi:[0,1]
	v_pk_mul_f32 v[48:49], v[30:31], v[80:81]
	v_pk_mul_f32 v[46:47], v[28:29], v[18:19]
	v_lshlrev_b32_e32 v18, 16, v82
	v_and_b32_e32 v19, 0xffff0000, v82
	v_lshlrev_b32_e32 v82, 16, v83
	v_and_b32_e32 v83, 0xffff0000, v83
	v_pk_mul_f32 v[18:19], v[16:17], v[18:19] op_sel_hi:[0,1]
	v_pk_mul_f32 v[82:83], v[16:17], v[82:83] op_sel_hi:[0,1]
	v_pk_mul_f32 v[52:53], v[34:35], v[82:83]
	v_pk_mul_f32 v[50:51], v[32:33], v[18:19]
	global_store_dwordx4 v[6:7], v[10:13], off offset:-2048
	global_store_dwordx4 v[6:7], v[42:45], off offset:-1024
	global_store_dwordx4 v[6:7], v[46:49], off
	global_store_dwordx4 v[6:7], v[50:53], off offset:1024
	v_lshl_add_u64 v[6:7], v[6:7], 0, s[6:7]
	s_waitcnt vmcnt(28)
	ds_swizzle_b32 v16, v135 offset:swizzle(SWAP,1)
	s_waitcnt lgkmcnt(0)
	v_add_f32_e32 v9, v135, v16
	ds_swizzle_b32 v16, v9 offset:swizzle(SWAP,2)
	s_waitcnt lgkmcnt(0)
	v_add_f32_e32 v9, v9, v16
	ds_swizzle_b32 v16, v9 offset:swizzle(SWAP,4)
	s_waitcnt lgkmcnt(0)
	v_add_f32_e32 v9, v9, v16
	ds_swizzle_b32 v16, v9 offset:swizzle(SWAP,8)
	s_waitcnt lgkmcnt(0)
	v_add_f32_e32 v9, v9, v16
	ds_swizzle_b32 v16, v9 offset:swizzle(SWAP,16)
	s_waitcnt lgkmcnt(0)
	v_add_f32_e32 v9, v9, v16
	v_mov_b32_e32 v16, v9
	s_nop 1
	v_permlane32_swap_b32_e32 v9, v16
	v_add_f32_e32 v9, v9, v16
	v_fmamk_f32 v9, v9, 0x3a800000, v8
	v_mul_f32_e32 v16, 0x4b800000, v9
	v_cmp_gt_f32_e64 s[0:1], s9, v9
	v_lshlrev_b32_e32 v18, 16, v84
	v_cndmask_b32_e64 v9, v9, v16, s[0:1]
	v_rsq_f32_e32 v9, v9
	v_and_b32_e32 v19, 0xffff0000, v84
	v_lshlrev_b32_e32 v84, 16, v85
	v_and_b32_e32 v85, 0xffff0000, v85
	v_mul_f32_e32 v16, 0x45800000, v9
	v_cndmask_b32_e64 v16, v9, v16, s[0:1]
	v_pk_mul_f32 v[18:19], v[16:17], v[18:19] op_sel_hi:[0,1]
	v_pk_mul_f32 v[84:85], v[16:17], v[84:85] op_sel_hi:[0,1]
	v_pk_mul_f32 v[12:13], v[22:23], v[84:85]
	v_pk_mul_f32 v[10:11], v[20:21], v[18:19]
	v_lshlrev_b32_e32 v18, 16, v86
	v_and_b32_e32 v19, 0xffff0000, v86
	v_lshlrev_b32_e32 v86, 16, v87
	v_and_b32_e32 v87, 0xffff0000, v87
	v_pk_mul_f32 v[18:19], v[16:17], v[18:19] op_sel_hi:[0,1]
	v_pk_mul_f32 v[86:87], v[16:17], v[86:87] op_sel_hi:[0,1]
	v_pk_mul_f32 v[44:45], v[26:27], v[86:87]
	v_pk_mul_f32 v[42:43], v[24:25], v[18:19]
	v_lshlrev_b32_e32 v18, 16, v88
	v_and_b32_e32 v19, 0xffff0000, v88
	v_lshlrev_b32_e32 v88, 16, v89
	v_and_b32_e32 v89, 0xffff0000, v89
	v_pk_mul_f32 v[18:19], v[16:17], v[18:19] op_sel_hi:[0,1]
	v_pk_mul_f32 v[88:89], v[16:17], v[88:89] op_sel_hi:[0,1]
	v_pk_mul_f32 v[48:49], v[30:31], v[88:89]
	v_pk_mul_f32 v[46:47], v[28:29], v[18:19]
	v_lshlrev_b32_e32 v18, 16, v90
	v_and_b32_e32 v19, 0xffff0000, v90
	v_lshlrev_b32_e32 v90, 16, v91
	v_and_b32_e32 v91, 0xffff0000, v91
	v_pk_mul_f32 v[18:19], v[16:17], v[18:19] op_sel_hi:[0,1]
	v_pk_mul_f32 v[90:91], v[16:17], v[90:91] op_sel_hi:[0,1]
	v_pk_mul_f32 v[52:53], v[34:35], v[90:91]
	v_pk_mul_f32 v[50:51], v[32:33], v[18:19]
	global_store_dwordx4 v[6:7], v[10:13], off offset:-2048
	global_store_dwordx4 v[6:7], v[42:45], off offset:-1024
	global_store_dwordx4 v[6:7], v[46:49], off
	global_store_dwordx4 v[6:7], v[50:53], off offset:1024
	v_lshl_add_u64 v[6:7], v[6:7], 0, s[6:7]
	s_waitcnt vmcnt(28)
	ds_swizzle_b32 v16, v136 offset:swizzle(SWAP,1)
	s_waitcnt lgkmcnt(0)
	v_add_f32_e32 v9, v136, v16
	ds_swizzle_b32 v16, v9 offset:swizzle(SWAP,2)
	s_waitcnt lgkmcnt(0)
	v_add_f32_e32 v9, v9, v16
	ds_swizzle_b32 v16, v9 offset:swizzle(SWAP,4)
	s_waitcnt lgkmcnt(0)
	v_add_f32_e32 v9, v9, v16
	ds_swizzle_b32 v16, v9 offset:swizzle(SWAP,8)
	s_waitcnt lgkmcnt(0)
	v_add_f32_e32 v9, v9, v16
	ds_swizzle_b32 v16, v9 offset:swizzle(SWAP,16)
	s_waitcnt lgkmcnt(0)
	v_add_f32_e32 v9, v9, v16
	v_mov_b32_e32 v16, v9
	s_nop 1
	v_permlane32_swap_b32_e32 v9, v16
	v_add_f32_e32 v9, v9, v16
	v_fmamk_f32 v9, v9, 0x3a800000, v8
	v_mul_f32_e32 v16, 0x4b800000, v9
	v_cmp_gt_f32_e64 s[0:1], s9, v9
	v_lshlrev_b32_e32 v18, 16, v92
	v_cndmask_b32_e64 v9, v9, v16, s[0:1]
	v_rsq_f32_e32 v9, v9
	v_and_b32_e32 v19, 0xffff0000, v92
	v_lshlrev_b32_e32 v92, 16, v93
	v_and_b32_e32 v93, 0xffff0000, v93
	v_mul_f32_e32 v16, 0x45800000, v9
	v_cndmask_b32_e64 v16, v9, v16, s[0:1]
	v_pk_mul_f32 v[18:19], v[16:17], v[18:19] op_sel_hi:[0,1]
	v_pk_mul_f32 v[92:93], v[16:17], v[92:93] op_sel_hi:[0,1]
	v_pk_mul_f32 v[12:13], v[22:23], v[92:93]
	v_pk_mul_f32 v[10:11], v[20:21], v[18:19]
	v_lshlrev_b32_e32 v18, 16, v94
	v_and_b32_e32 v19, 0xffff0000, v94
	v_lshlrev_b32_e32 v94, 16, v95
	v_and_b32_e32 v95, 0xffff0000, v95
	v_pk_mul_f32 v[18:19], v[16:17], v[18:19] op_sel_hi:[0,1]
	v_pk_mul_f32 v[94:95], v[16:17], v[94:95] op_sel_hi:[0,1]
	v_pk_mul_f32 v[44:45], v[26:27], v[94:95]
	v_pk_mul_f32 v[42:43], v[24:25], v[18:19]
	v_lshlrev_b32_e32 v18, 16, v96
	v_and_b32_e32 v19, 0xffff0000, v96
	v_lshlrev_b32_e32 v96, 16, v97
	v_and_b32_e32 v97, 0xffff0000, v97
	v_pk_mul_f32 v[18:19], v[16:17], v[18:19] op_sel_hi:[0,1]
	v_pk_mul_f32 v[96:97], v[16:17], v[96:97] op_sel_hi:[0,1]
	v_pk_mul_f32 v[48:49], v[30:31], v[96:97]
	v_pk_mul_f32 v[46:47], v[28:29], v[18:19]
	v_lshlrev_b32_e32 v18, 16, v98
	v_and_b32_e32 v19, 0xffff0000, v98
	v_lshlrev_b32_e32 v98, 16, v99
	v_and_b32_e32 v99, 0xffff0000, v99
	v_pk_mul_f32 v[18:19], v[16:17], v[18:19] op_sel_hi:[0,1]
	v_pk_mul_f32 v[98:99], v[16:17], v[98:99] op_sel_hi:[0,1]
	v_pk_mul_f32 v[52:53], v[34:35], v[98:99]
	v_pk_mul_f32 v[50:51], v[32:33], v[18:19]
	global_store_dwordx4 v[6:7], v[10:13], off offset:-2048
	global_store_dwordx4 v[6:7], v[42:45], off offset:-1024
	global_store_dwordx4 v[6:7], v[46:49], off
	global_store_dwordx4 v[6:7], v[50:53], off offset:1024
	v_lshl_add_u64 v[6:7], v[6:7], 0, s[6:7]
	s_waitcnt vmcnt(28)
	ds_swizzle_b32 v16, v137 offset:swizzle(SWAP,1)
	s_waitcnt lgkmcnt(0)
	v_add_f32_e32 v9, v137, v16
	ds_swizzle_b32 v16, v9 offset:swizzle(SWAP,2)
	s_waitcnt lgkmcnt(0)
	v_add_f32_e32 v9, v9, v16
	ds_swizzle_b32 v16, v9 offset:swizzle(SWAP,4)
	s_waitcnt lgkmcnt(0)
	v_add_f32_e32 v9, v9, v16
	ds_swizzle_b32 v16, v9 offset:swizzle(SWAP,8)
	s_waitcnt lgkmcnt(0)
	v_add_f32_e32 v9, v9, v16
	ds_swizzle_b32 v16, v9 offset:swizzle(SWAP,16)
	s_waitcnt lgkmcnt(0)
	v_add_f32_e32 v9, v9, v16
	v_mov_b32_e32 v16, v9
	s_nop 1
	v_permlane32_swap_b32_e32 v9, v16
	v_add_f32_e32 v9, v9, v16
	v_fmamk_f32 v9, v9, 0x3a800000, v8
	v_mul_f32_e32 v16, 0x4b800000, v9
	v_cmp_gt_f32_e64 s[0:1], s9, v9
	v_lshlrev_b32_e32 v18, 16, v100
	v_cndmask_b32_e64 v9, v9, v16, s[0:1]
	v_rsq_f32_e32 v9, v9
	v_and_b32_e32 v19, 0xffff0000, v100
	v_lshlrev_b32_e32 v100, 16, v101
	v_and_b32_e32 v101, 0xffff0000, v101
	v_mul_f32_e32 v16, 0x45800000, v9
	v_cndmask_b32_e64 v16, v9, v16, s[0:1]
	v_pk_mul_f32 v[18:19], v[16:17], v[18:19] op_sel_hi:[0,1]
	v_pk_mul_f32 v[100:101], v[16:17], v[100:101] op_sel_hi:[0,1]
	v_pk_mul_f32 v[12:13], v[22:23], v[100:101]
	v_pk_mul_f32 v[10:11], v[20:21], v[18:19]
	v_lshlrev_b32_e32 v18, 16, v102
	v_and_b32_e32 v19, 0xffff0000, v102
	v_lshlrev_b32_e32 v102, 16, v103
	v_and_b32_e32 v103, 0xffff0000, v103
	v_pk_mul_f32 v[18:19], v[16:17], v[18:19] op_sel_hi:[0,1]
	v_pk_mul_f32 v[102:103], v[16:17], v[102:103] op_sel_hi:[0,1]
	v_pk_mul_f32 v[44:45], v[26:27], v[102:103]
	v_pk_mul_f32 v[42:43], v[24:25], v[18:19]
	v_lshlrev_b32_e32 v18, 16, v104
	v_and_b32_e32 v19, 0xffff0000, v104
	v_lshlrev_b32_e32 v104, 16, v105
	v_and_b32_e32 v105, 0xffff0000, v105
	v_pk_mul_f32 v[18:19], v[16:17], v[18:19] op_sel_hi:[0,1]
	v_pk_mul_f32 v[104:105], v[16:17], v[104:105] op_sel_hi:[0,1]
	v_pk_mul_f32 v[48:49], v[30:31], v[104:105]
	v_pk_mul_f32 v[46:47], v[28:29], v[18:19]
	v_lshlrev_b32_e32 v18, 16, v106
	v_and_b32_e32 v19, 0xffff0000, v106
	v_lshlrev_b32_e32 v106, 16, v107
	v_and_b32_e32 v107, 0xffff0000, v107
	v_pk_mul_f32 v[18:19], v[16:17], v[18:19] op_sel_hi:[0,1]
	v_pk_mul_f32 v[106:107], v[16:17], v[106:107] op_sel_hi:[0,1]
	v_pk_mul_f32 v[52:53], v[34:35], v[106:107]
	v_pk_mul_f32 v[50:51], v[32:33], v[18:19]
	global_store_dwordx4 v[6:7], v[10:13], off offset:-2048
	global_store_dwordx4 v[6:7], v[42:45], off offset:-1024
	global_store_dwordx4 v[6:7], v[46:49], off
	global_store_dwordx4 v[6:7], v[50:53], off offset:1024
	v_lshl_add_u64 v[6:7], v[6:7], 0, s[6:7]
	s_waitcnt vmcnt(28)
	ds_swizzle_b32 v16, v138 offset:swizzle(SWAP,1)
	s_waitcnt lgkmcnt(0)
	v_add_f32_e32 v9, v138, v16
	ds_swizzle_b32 v16, v9 offset:swizzle(SWAP,2)
	s_waitcnt lgkmcnt(0)
	v_add_f32_e32 v9, v9, v16
	ds_swizzle_b32 v16, v9 offset:swizzle(SWAP,4)
	s_waitcnt lgkmcnt(0)
	v_add_f32_e32 v9, v9, v16
	ds_swizzle_b32 v16, v9 offset:swizzle(SWAP,8)
	s_waitcnt lgkmcnt(0)
	v_add_f32_e32 v9, v9, v16
	ds_swizzle_b32 v16, v9 offset:swizzle(SWAP,16)
	s_waitcnt lgkmcnt(0)
	v_add_f32_e32 v9, v9, v16
	v_mov_b32_e32 v16, v9
	s_nop 1
	v_permlane32_swap_b32_e32 v9, v16
	v_add_f32_e32 v9, v9, v16
	v_fmamk_f32 v9, v9, 0x3a800000, v8
	v_mul_f32_e32 v16, 0x4b800000, v9
	v_cmp_gt_f32_e64 s[0:1], s9, v9
	v_lshlrev_b32_e32 v18, 16, v108
	v_cndmask_b32_e64 v9, v9, v16, s[0:1]
	v_rsq_f32_e32 v9, v9
	v_and_b32_e32 v19, 0xffff0000, v108
	v_lshlrev_b32_e32 v108, 16, v109
	v_and_b32_e32 v109, 0xffff0000, v109
	v_mul_f32_e32 v16, 0x45800000, v9
	v_cndmask_b32_e64 v16, v9, v16, s[0:1]
	v_pk_mul_f32 v[18:19], v[16:17], v[18:19] op_sel_hi:[0,1]
	v_pk_mul_f32 v[108:109], v[16:17], v[108:109] op_sel_hi:[0,1]
	v_pk_mul_f32 v[12:13], v[22:23], v[108:109]
	v_pk_mul_f32 v[10:11], v[20:21], v[18:19]
	v_lshlrev_b32_e32 v18, 16, v110
	v_and_b32_e32 v19, 0xffff0000, v110
	v_lshlrev_b32_e32 v110, 16, v111
	v_and_b32_e32 v111, 0xffff0000, v111
	v_pk_mul_f32 v[18:19], v[16:17], v[18:19] op_sel_hi:[0,1]
	v_pk_mul_f32 v[110:111], v[16:17], v[110:111] op_sel_hi:[0,1]
	v_pk_mul_f32 v[44:45], v[26:27], v[110:111]
	v_pk_mul_f32 v[42:43], v[24:25], v[18:19]
	v_lshlrev_b32_e32 v18, 16, v112
	v_and_b32_e32 v19, 0xffff0000, v112
	v_lshlrev_b32_e32 v112, 16, v113
	v_and_b32_e32 v113, 0xffff0000, v113
	v_pk_mul_f32 v[18:19], v[16:17], v[18:19] op_sel_hi:[0,1]
	v_pk_mul_f32 v[112:113], v[16:17], v[112:113] op_sel_hi:[0,1]
	v_pk_mul_f32 v[48:49], v[30:31], v[112:113]
	v_pk_mul_f32 v[46:47], v[28:29], v[18:19]
	v_lshlrev_b32_e32 v18, 16, v114
	v_and_b32_e32 v19, 0xffff0000, v114
	v_lshlrev_b32_e32 v114, 16, v115
	v_and_b32_e32 v115, 0xffff0000, v115
	v_pk_mul_f32 v[18:19], v[16:17], v[18:19] op_sel_hi:[0,1]
	v_pk_mul_f32 v[114:115], v[16:17], v[114:115] op_sel_hi:[0,1]
	v_pk_mul_f32 v[52:53], v[34:35], v[114:115]
	v_pk_mul_f32 v[50:51], v[32:33], v[18:19]
	global_store_dwordx4 v[6:7], v[10:13], off offset:-2048
	global_store_dwordx4 v[6:7], v[42:45], off offset:-1024
	global_store_dwordx4 v[6:7], v[46:49], off
	global_store_dwordx4 v[6:7], v[50:53], off offset:1024
	v_lshl_add_u64 v[6:7], v[6:7], 0, s[6:7]
	s_waitcnt vmcnt(28)
	ds_swizzle_b32 v16, v139 offset:swizzle(SWAP,1)
	s_waitcnt lgkmcnt(0)
	v_add_f32_e32 v9, v139, v16
	ds_swizzle_b32 v16, v9 offset:swizzle(SWAP,2)
	s_waitcnt lgkmcnt(0)
	v_add_f32_e32 v9, v9, v16
	ds_swizzle_b32 v16, v9 offset:swizzle(SWAP,4)
	s_waitcnt lgkmcnt(0)
	v_add_f32_e32 v9, v9, v16
	ds_swizzle_b32 v16, v9 offset:swizzle(SWAP,8)
	s_waitcnt lgkmcnt(0)
	v_add_f32_e32 v9, v9, v16
	ds_swizzle_b32 v16, v9 offset:swizzle(SWAP,16)
	s_waitcnt lgkmcnt(0)
	v_add_f32_e32 v9, v9, v16
	v_mov_b32_e32 v16, v9
	s_nop 1
	v_permlane32_swap_b32_e32 v9, v16
	v_add_f32_e32 v9, v9, v16
	v_fmamk_f32 v9, v9, 0x3a800000, v8
	v_mul_f32_e32 v16, 0x4b800000, v9
	v_cmp_gt_f32_e64 s[0:1], s9, v9
	v_lshlrev_b32_e32 v18, 16, v116
	v_cndmask_b32_e64 v9, v9, v16, s[0:1]
	v_rsq_f32_e32 v9, v9
	v_and_b32_e32 v19, 0xffff0000, v116
	v_lshlrev_b32_e32 v116, 16, v117
	v_and_b32_e32 v117, 0xffff0000, v117
	v_mul_f32_e32 v16, 0x45800000, v9
	v_cndmask_b32_e64 v16, v9, v16, s[0:1]
	v_pk_mul_f32 v[18:19], v[16:17], v[18:19] op_sel_hi:[0,1]
	v_pk_mul_f32 v[116:117], v[16:17], v[116:117] op_sel_hi:[0,1]
	v_pk_mul_f32 v[12:13], v[22:23], v[116:117]
	v_pk_mul_f32 v[10:11], v[20:21], v[18:19]
	v_lshlrev_b32_e32 v18, 16, v118
	v_and_b32_e32 v19, 0xffff0000, v118
	v_lshlrev_b32_e32 v118, 16, v119
	v_and_b32_e32 v119, 0xffff0000, v119
	v_pk_mul_f32 v[18:19], v[16:17], v[18:19] op_sel_hi:[0,1]
	v_pk_mul_f32 v[118:119], v[16:17], v[118:119] op_sel_hi:[0,1]
	v_pk_mul_f32 v[44:45], v[26:27], v[118:119]
	v_pk_mul_f32 v[42:43], v[24:25], v[18:19]
	v_lshlrev_b32_e32 v18, 16, v120
	v_and_b32_e32 v19, 0xffff0000, v120
	v_lshlrev_b32_e32 v120, 16, v121
	v_and_b32_e32 v121, 0xffff0000, v121
	v_pk_mul_f32 v[18:19], v[16:17], v[18:19] op_sel_hi:[0,1]
	v_pk_mul_f32 v[120:121], v[16:17], v[120:121] op_sel_hi:[0,1]
	v_pk_mul_f32 v[48:49], v[30:31], v[120:121]
	v_pk_mul_f32 v[46:47], v[28:29], v[18:19]
	v_lshlrev_b32_e32 v18, 16, v122
	v_and_b32_e32 v19, 0xffff0000, v122
	v_lshlrev_b32_e32 v122, 16, v123
	v_and_b32_e32 v123, 0xffff0000, v123
	v_pk_mul_f32 v[18:19], v[16:17], v[18:19] op_sel_hi:[0,1]
	v_pk_mul_f32 v[122:123], v[16:17], v[122:123] op_sel_hi:[0,1]
	v_pk_mul_f32 v[52:53], v[34:35], v[122:123]
	v_pk_mul_f32 v[50:51], v[32:33], v[18:19]
	global_store_dwordx4 v[6:7], v[10:13], off offset:-2048
	global_store_dwordx4 v[6:7], v[42:45], off offset:-1024
	global_store_dwordx4 v[6:7], v[46:49], off
	global_store_dwordx4 v[6:7], v[50:53], off offset:1024
	v_lshl_add_u64 v[6:7], v[6:7], 0, s[6:7]
	s_branch .LBB0_1388
.Lfn_generic:
	v_mov_b32_e32 v54, 0
	s_and_saveexec_b64 s[0:1], vcc
	global_load_dword v54, v[2:3], off
	s_or_b64 exec, exec, s[0:1]
	global_load_dwordx2 v[14:15], v[4:5], off offset:-1024
	global_load_dwordx2 v[36:37], v[4:5], off offset:-512
	global_load_dwordx2 v[38:39], v[4:5], off
	global_load_dwordx2 v[40:41], v[4:5], off offset:512
	v_lshl_add_u64 v[2:3], v[2:3], 0, s[2:3]
	v_lshl_add_u64 v[4:5], v[4:5], 0, s[4:5]
	s_waitcnt vmcnt(0)
.Lfn_loop:
	s_waitcnt vmcnt(4)
	s_add_i32 s8, s8, s12
	ds_swizzle_b32 v16, v54 offset:swizzle(SWAP,1)
	s_waitcnt lgkmcnt(0)
	v_add_f32_e32 v9, v54, v16
	ds_swizzle_b32 v16, v9 offset:swizzle(SWAP,2)
	s_waitcnt lgkmcnt(0)
	v_add_f32_e32 v9, v9, v16
	ds_swizzle_b32 v16, v9 offset:swizzle(SWAP,4)
	s_waitcnt lgkmcnt(0)
	v_add_f32_e32 v9, v9, v16
	ds_swizzle_b32 v16, v9 offset:swizzle(SWAP,8)
	s_waitcnt lgkmcnt(0)
	v_add_f32_e32 v9, v9, v16
	ds_swizzle_b32 v16, v9 offset:swizzle(SWAP,16)
	s_waitcnt lgkmcnt(0)
	v_add_f32_e32 v9, v9, v16
	v_mov_b32_e32 v16, v9
	s_nop 1
	v_permlane32_swap_b32_e32 v9, v16
	v_add_f32_e32 v9, v9, v16
	v_fmamk_f32 v9, v9, 0x3a800000, v8
	v_mul_f32_e32 v16, 0x4b800000, v9
	v_cmp_gt_f32_e64 s[0:1], s9, v9
	v_lshlrev_b32_e32 v18, 16, v14
	v_cndmask_b32_e64 v9, v9, v16, s[0:1]
	v_rsq_f32_e32 v9, v9
	v_and_b32_e32 v19, 0xffff0000, v14
	v_lshlrev_b32_e32 v14, 16, v15
	v_and_b32_e32 v15, 0xffff0000, v15
	v_mul_f32_e32 v16, 0x45800000, v9
	v_cndmask_b32_e64 v16, v9, v16, s[0:1]
	v_pk_mul_f32 v[18:19], v[16:17], v[18:19] op_sel_hi:[0,1]
	v_pk_mul_f32 v[14:15], v[16:17], v[14:15] op_sel_hi:[0,1]
	v_pk_mul_f32 v[12:13], v[22:23], v[14:15]
	v_pk_mul_f32 v[10:11], v[20:21], v[18:19]
	v_lshlrev_b32_e32 v18, 16, v36
	v_and_b32_e32 v19, 0xffff0000, v36
	v_lshlrev_b32_e32 v36, 16, v37
	v_and_b32_e32 v37, 0xffff0000, v37
	v_pk_mul_f32 v[18:19], v[16:17], v[18:19] op_sel_hi:[0,1]
	v_pk_mul_f32 v[36:37], v[16:17], v[36:37] op_sel_hi:[0,1]
	v_pk_mul_f32 v[44:45], v[26:27], v[36:37]
	v_pk_mul_f32 v[42:43], v[24:25], v[18:19]
	v_lshlrev_b32_e32 v18, 16, v38
	v_and_b32_e32 v19, 0xffff0000, v38
	v_lshlrev_b32_e32 v38, 16, v39
	v_and_b32_e32 v39, 0xffff0000, v39
	v_pk_mul_f32 v[18:19], v[16:17], v[18:19] op_sel_hi:[0,1]
	v_pk_mul_f32 v[38:39], v[16:17], v[38:39] op_sel_hi:[0,1]
	v_pk_mul_f32 v[48:49], v[30:31], v[38:39]
	v_pk_mul_f32 v[46:47], v[28:29], v[18:19]
	v_lshlrev_b32_e32 v18, 16, v40
	v_and_b32_e32 v19, 0xffff0000, v40
	v_lshlrev_b32_e32 v40, 16, v41
	v_and_b32_e32 v41, 0xffff0000, v41
	v_pk_mul_f32 v[18:19], v[16:17], v[18:19] op_sel_hi:[0,1]
	v_pk_mul_f32 v[40:41], v[16:17], v[40:41] op_sel_hi:[0,1]
	v_pk_mul_f32 v[52:53], v[34:35], v[40:41]
	v_pk_mul_f32 v[50:51], v[32:33], v[18:19]
	s_cmpk_gt_i32 s8, 0x3fff
	s_cbranch_scc1 .Lfn_skip
	s_and_saveexec_b64 s[0:1], vcc
	global_load_dword v54, v[2:3], off
	s_or_b64 exec, exec, s[0:1]
	global_load_dwordx2 v[14:15], v[4:5], off offset:-1024
	global_load_dwordx2 v[36:37], v[4:5], off offset:-512
	global_load_dwordx2 v[38:39], v[4:5], off
	global_load_dwordx2 v[40:41], v[4:5], off offset:512
	v_lshl_add_u64 v[2:3], v[2:3], 0, s[2:3]
	v_lshl_add_u64 v[4:5], v[4:5], 0, s[4:5]
